# differential attention: waves whose 32 queries are all padding positions skip their key tiles and always vote for the exact early exit (on v107)
# baseline (speedup 1.0000x reference)
.LBB0_298:
	s_or_b64 exec, exec, s[4:5]
	v_mov_b32_e32 v1, s33
	s_waitcnt lgkmcnt(0)
	s_barrier
	ds_read_b32 v1, v1
	s_movk_i32 s4, 0x43f
	s_waitcnt lgkmcnt(0)
	v_cmp_lt_i32_e32 vcc, s4, v1
	v_readfirstlane_b32 s6, v1
	s_mov_b64 s[4:5], -1
	s_cbranch_vccnz .LBB0_293
	s_and_b32 s16, s6, 15
	s_bfe_u32 s4, s6, 0x20004
	s_lshl_b32 s7, s16, 4
	v_readlane_b32 s8, v254, 43
	s_lshl_b32 s6, s6, 1
	s_or_b32 s7, s7, s8
	s_and_b32 s8, s6, 0xffffff80
	v_mov_b32_e32 v187, v202
	s_sub_i32 s37, 0x800, s8
	s_add_i32 s54, s37, s63
	v_and_b32_e32 v186, 31, v187
	v_or_b32_e32 v2, s54, v186
	s_mulk_i32 s4, 0x810
	s_mov_b32 s5, s89
	v_ashrrev_i32_e32 v3, 31, v2
	v_lshl_add_u64 v[6:7], v[2:3], 0, s[4:5]
	v_mov_b32_e32 v1, s7
	v_lshlrev_b64 v[6:7], 13, v[6:7]
	v_readlane_b32 s6, v254, 48
	v_ashrrev_i32_e32 v201, 5, v187
	v_lshl_add_u64 v[6:7], s[10:11], 0, v[6:7]
	s_lshl_b32 s88, s16, 8
	v_readlane_b32 s7, v254, 49
	v_lshl_add_u64 v[6:7], v[6:7], 0, s[88:89]
	s_mov_b32 s7, s89
	v_lshlrev_b32_e32 v188, 3, v201
	v_lshl_add_u64 v[6:7], v[6:7], 0, s[6:7]
	v_ashrrev_i32_e32 v189, 31, v188
	v_lshl_add_u64 v[6:7], v[188:189], 1, v[6:7]
	global_load_dwordx2 v[4:5], v1, s[76:77] offset:2048
	global_load_dwordx4 v[116:119], v[6:7], off
	global_load_dwordx4 v[120:123], v[6:7], off offset:32
	global_load_dwordx4 v[124:127], v[6:7], off offset:64
	global_load_dwordx4 v[128:131], v[6:7], off offset:96
	s_mov_b32 s38, s6
	v_writelane_b32 v254, s38, 48
	s_lshl_b32 s9, s16, 7
	v_writelane_b32 v254, s39, 49
	s_mov_b64 s[6:7], exec
	v_readlane_b32 s38, v254, 51
	v_readlane_b32 s39, v254, 52
	s_and_b64 s[38:39], s[6:7], s[38:39]
	s_mov_b64 exec, s[38:39]
	ds_write_b32 v203, v0
	s_or_b64 exec, exec, s[6:7]
	s_add_i32 s5, s54, -16
	s_lshr_b32 s6, s54, 6
	s_add_i32 s42, s16, 1
	s_lshr_b32 s5, s5, 6
	s_add_i32 s6, s6, 1
	s_cmp_gt_i32 s54, -1
	s_cselect_b32 s6, s6, 0
	s_lshl_b32 s7, s6, 6
	s_lshl_b32 s6, s6, 1
	s_cmpk_lt_u32 s7, 0x880
	s_cselect_b32 s55, s6, 0x43
	s_cmpk_gt_i32 s54, 0x81f
	s_cselect_b32 s55, 0, s55
	s_mov_b32 s98, 0xf149f2ca
	s_cselect_b32 s98, 0x7149f2ca, s98
	s_sub_i32 s6, 0x900, s8
	s_lshr_b32 s6, s6, 7
	s_add_i32 s38, s6, -1
	v_lshrrev_b32_e32 v6, 3, v164
	v_or_b32_e32 v8, s9, v165
	s_lshl_b32 s88, s4, 1
	v_add_lshl_u32 v6, s4, v6, 13
	v_mov_b32_e32 v7, v0
	v_mul_u32_u24_e32 v8, 0x2200, v8
	s_cmp_gt_i32 s54, 15
	v_lshl_add_u64 v[6:7], s[10:11], 0, v[6:7]
	v_lshlrev_b32_e32 v8, 1, v8
	v_mov_b32_e32 v9, v0
	s_cselect_b64 s[16:17], -1, 0
	s_lshl_b32 s6, s9, 1
	s_mov_b32 s7, s89
	v_lshl_add_u64 v[8:9], s[86:87], 0, v[8:9]
	s_cmpk_lt_u32 s37, 0x800
	v_lshl_add_u64 v[6:7], v[6:7], 0, s[6:7]
	v_mov_b32_e32 v169, v0
	v_lshl_add_u64 v[8:9], v[8:9], 0, s[88:89]
	s_cselect_b32 s88, s38, 16
	v_lshl_add_u64 v[6:7], v[6:7], 0, v[168:169]
	s_mov_b64 s[38:39], 0x1000
	v_mov_b32_e32 v167, v0
	v_lshl_add_u64 v[192:193], v[6:7], 0, s[38:39]
	s_lshl_b64 s[38:39], s[88:89], 20
	v_lshl_add_u64 v[190:191], v[8:9], 0, v[166:167]
	v_lshl_add_u64 v[6:7], v[192:193], 0, s[38:39]
	s_mov_b64 s[40:41], 0x88000
	v_add_co_u32_e32 v8, vcc, s24, v6
	s_lshl_b64 s[38:39], s[88:89], 8
	v_lshl_add_u64 v[194:195], v[190:191], 0, s[40:41]
	s_mov_b64 s[40:41], 0x110000
	v_addc_co_u32_e32 v9, vcc, 0, v7, vcc
	global_load_dwordx4 v[132:135], v[6:7], off
	global_load_dwordx4 v[136:139], v[6:7], off offset:128
	global_load_dwordx4 v[140:143], v[8:9], off
	global_load_dwordx4 v[144:147], v[8:9], off offset:128
	v_lshl_add_u64 v[6:7], v[190:191], 0, s[38:39]
	v_lshl_add_u64 v[196:197], v[190:191], 0, s[40:41]
	s_mov_b64 s[40:41], 0x198000
	v_lshl_add_u64 v[8:9], v[194:195], 0, s[38:39]
	global_load_dwordx4 v[148:151], v[6:7], off
	global_load_dwordx4 v[152:155], v[8:9], off
	v_lshl_add_u64 v[6:7], v[196:197], 0, s[38:39]
	v_lshl_add_u64 v[198:199], v[190:191], 0, s[40:41]
	v_lshl_add_u64 v[8:9], v[198:199], 0, s[38:39]
	global_load_dwordx4 v[156:159], v[6:7], off
	global_load_dwordx4 v[160:163], v[8:9], off
	s_waitcnt vmcnt(11)
	v_and_b32_e32 v1, 0xffff0000, v116
	v_lshlrev_b32_e32 v3, 16, v116
	v_mul_f32_e32 v1, v1, v1
	v_fmac_f32_e32 v1, v3, v3
	v_lshlrev_b32_e32 v3, 16, v117
	v_fmac_f32_e32 v1, v3, v3
	v_and_b32_e32 v3, 0xffff0000, v117
	v_fmac_f32_e32 v1, v3, v3
	v_lshlrev_b32_e32 v3, 16, v118
	v_fmac_f32_e32 v1, v3, v3
	v_and_b32_e32 v3, 0xffff0000, v118
	v_fmac_f32_e32 v1, v3, v3
	v_lshlrev_b32_e32 v3, 16, v119
	v_fmac_f32_e32 v1, v3, v3
	v_and_b32_e32 v3, 0xffff0000, v119
	v_fmac_f32_e32 v1, v3, v3
	s_waitcnt vmcnt(10)
	v_lshlrev_b32_e32 v3, 16, v120
	v_fmac_f32_e32 v1, v3, v3
	v_and_b32_e32 v3, 0xffff0000, v120
	v_fmac_f32_e32 v1, v3, v3
	v_lshlrev_b32_e32 v3, 16, v121
	v_fmac_f32_e32 v1, v3, v3
	v_and_b32_e32 v3, 0xffff0000, v121
	v_fmac_f32_e32 v1, v3, v3
	v_lshlrev_b32_e32 v3, 16, v122
	v_fmac_f32_e32 v1, v3, v3
	v_and_b32_e32 v3, 0xffff0000, v122
	v_fmac_f32_e32 v1, v3, v3
	v_lshlrev_b32_e32 v3, 16, v123
	v_fmac_f32_e32 v1, v3, v3
	v_and_b32_e32 v3, 0xffff0000, v123
	v_fmac_f32_e32 v1, v3, v3
	s_waitcnt vmcnt(9)
	v_lshlrev_b32_e32 v3, 16, v124
	v_fmac_f32_e32 v1, v3, v3
	v_and_b32_e32 v3, 0xffff0000, v124
	v_fmac_f32_e32 v1, v3, v3
	v_lshlrev_b32_e32 v3, 16, v125
	v_fmac_f32_e32 v1, v3, v3
	v_and_b32_e32 v3, 0xffff0000, v125
	v_fmac_f32_e32 v1, v3, v3
	v_lshlrev_b32_e32 v3, 16, v126
	v_fmac_f32_e32 v1, v3, v3
	v_and_b32_e32 v3, 0xffff0000, v126
	v_fmac_f32_e32 v1, v3, v3
	v_lshlrev_b32_e32 v3, 16, v127
	v_fmac_f32_e32 v1, v3, v3
	v_and_b32_e32 v3, 0xffff0000, v127
	v_fmac_f32_e32 v1, v3, v3
	s_waitcnt vmcnt(8)
	v_lshlrev_b32_e32 v3, 16, v128
	v_fmac_f32_e32 v1, v3, v3
	v_and_b32_e32 v3, 0xffff0000, v128
	v_fmac_f32_e32 v1, v3, v3
	v_lshlrev_b32_e32 v3, 16, v129
	v_fmac_f32_e32 v1, v3, v3
	v_and_b32_e32 v3, 0xffff0000, v129
	v_fmac_f32_e32 v1, v3, v3
	v_lshlrev_b32_e32 v3, 16, v130
	v_fmac_f32_e32 v1, v3, v3
	v_and_b32_e32 v3, 0xffff0000, v130
	v_fmac_f32_e32 v1, v3, v3
	v_lshlrev_b32_e32 v3, 16, v131
	v_fmac_f32_e32 v1, v3, v3
	v_and_b32_e32 v3, 0xffff0000, v131
	v_fmac_f32_e32 v1, v3, v3
	ds_bpermute_b32 v3, v200, v1
	v_add_f32_e32 v4, v4, v5
	s_waitcnt lgkmcnt(0)
	v_add_f32_e32 v1, v1, v3
	v_mul_f32_e32 v1, v4, v1
	s_mov_b32 s9, 0xf800000
	v_add_u32_e32 v5, -16, v2
	v_mul_f32_e32 v3, 0x4f800000, v1
	v_cmp_gt_f32_e32 vcc, s9, v1
	v_lshrrev_b32_e32 v167, 6, v5
	v_cvt_f32_ubyte0_e32 v5, s42
	v_cndmask_b32_e32 v1, v1, v3, vcc
	v_mul_f32_e32 v5, -0.5, v5
	v_sqrt_f32_e32 v3, v1
	v_exp_f32_e32 v5, v5
	s_lshl_b32 s57, s88, 16
	s_and_b32 s9, s57, 0x10000
	v_add_u32_e32 v4, -1, v3
	v_mul_f32_e32 v214, 0xbfb8aa3b, v5
	v_fma_f32 v5, -v4, v3, v1
	v_cmp_ge_f32_e64 s[40:41], 0, v5
	v_add_u32_e32 v5, 1, v3
	v_lshlrev_b32_e32 v6, 1, v186
	v_cndmask_b32_e64 v4, v3, v4, s[40:41]
	v_fma_f32 v3, -v5, v3, v1
	v_cmp_lt_f32_e64 s[40:41], 0, v3
	v_lshrrev_b32_e32 v7, 1, v187
	v_and_b32_e32 v6, 8, v6
	v_cndmask_b32_e64 v3, v4, v5, s[40:41]
	v_mul_f32_e32 v4, 0x37800000, v3
	v_cndmask_b32_e32 v3, v3, v4, vcc
	v_mov_b32_e32 v4, 0x260
	v_cmp_class_f32_e32 vcc, v1, v4
	v_and_b32_e32 v7, 4, v7
	v_and_b32_e32 v8, 19, v187
	v_cndmask_b32_e32 v1, v3, v1, vcc
	v_mul_f32_e32 v1, 0x3e38aa3b, v1
	v_fmamk_f32 v215, v1, 0x3f8020c5, v208
	v_add_u32_e32 v1, s9, v204
	v_or3_b32 v6, v7, v8, v6
	v_lshrrev_b32_e32 v7, 1, v6
	v_cmp_gt_i32_e64 s[38:39], 16, v2
	s_waitcnt vmcnt(7)
	ds_write_b128 v1, v[132:135]
	s_waitcnt vmcnt(5)
	ds_write_b128 v1, v[140:143] offset:8192
	ds_write_b128 v1, v[136:139] offset:16384
	s_waitcnt vmcnt(4)
	ds_write_b128 v1, v[144:147] offset:24576
	s_waitcnt vmcnt(3)
	ds_write_b128 v1, v[148:151] offset:32768
	s_waitcnt vmcnt(2)
	ds_write_b128 v1, v[152:155] offset:40960
	s_waitcnt vmcnt(1)
	ds_write_b128 v1, v[156:159] offset:49152
	s_waitcnt vmcnt(0)
	ds_write_b128 v1, v[160:163] offset:57344
	v_cvt_f32_i32_e32 v1, v2
	v_bitop3_b32 v2, v7, v201, 7 bitop3:0x6c
	v_lshlrev_b32_e32 v232, 4, v2
	v_readlane_b32 s42, v254, 45
	v_mul_f32_e64 v231, -v214, v1
	v_add_u32_e32 v1, 2, v201
	v_bitop3_b32 v2, v7, v1, 7 bitop3:0x6c
	v_lshlrev_b32_e32 v233, 4, v2
	v_add_u32_e32 v2, 4, v201
	v_bitop3_b32 v3, v7, v2, 7 bitop3:0x6c
	v_lshlrev_b32_e32 v234, 4, v3
	v_add_u32_e32 v3, 6, v201
	v_bitop3_b32 v4, v7, v3, 7 bitop3:0x6c
	v_lshlrev_b32_e32 v235, 4, v4
	v_add_u32_e32 v4, 12, v201
	v_bitop3_b32 v4, v4, v187, 15 bitop3:0x78
	v_lshlrev_b32_e32 v236, 4, v4
	v_add_u32_e32 v4, 14, v201
	v_bitop3_b32 v4, v4, v187, 15 bitop3:0x78
	v_lshlrev_b32_e32 v237, 4, v4
	v_add_u32_e32 v4, 8, v201
	v_bitop3_b32 v1, v1, v187, 15 bitop3:0x78
	v_bitop3_b32 v4, v4, v187, 15 bitop3:0x78
	v_bitop3_b32 v2, v2, v187, 15 bitop3:0x78
	v_lshlrev_b32_e32 v243, 4, v1
	v_add_u32_e32 v1, s42, v186
	v_lshlrev_b32_e32 v238, 4, v4
	v_add_u32_e32 v4, 10, v201
	v_lshlrev_b32_e32 v240, 4, v2
	v_bitop3_b32 v2, v3, v187, 15 bitop3:0x78
	s_lshl_b32 s58, s88, 7
	v_sub_u32_e32 v1, v1, v188
	v_bitop3_b32 v4, v4, v187, 15 bitop3:0x78
	v_lshlrev_b32_e32 v241, 4, v2
	v_bitop3_b32 v2, v201, v187, 15 bitop3:0x78
	v_subrev_u32_e32 v1, s58, v1
	v_mov_b32_e32 v14, v0
	v_mov_b32_e32 v15, v0
	v_lshlrev_b32_e32 v213, 7, v6
	v_lshlrev_b32_e32 v239, 4, v4
	v_lshlrev_b32_e32 v242, 4, v2
	s_add_i32 s9, s88, -1
	v_subrev_u32_e32 v244, s8, v1
	v_mov_b32_e32 v1, v0
	v_mov_b32_e32 v2, v0
	v_mov_b32_e32 v3, v0
	v_mov_b32_e32 v4, v0
	v_mov_b32_e32 v5, v0
	v_mov_b32_e32 v6, v0
	v_mov_b32_e32 v7, v0
	v_mov_b32_e32 v8, v0
	v_mov_b32_e32 v9, v0
	v_mov_b32_e32 v10, v0
	v_mov_b32_e32 v11, v0
	v_mov_b32_e32 v12, v0
	v_mov_b32_e32 v13, v0
	v_mov_b64_e32 v[30:31], v[14:15]
	v_mov_b64_e32 v[46:47], v[14:15]
	v_mov_b64_e32 v[62:63], v[14:15]
	v_mov_b64_e32 v[78:79], v[14:15]
	s_mov_b32 s56, 1
	s_mov_b32 s7, 0
	v_lshlrev_b32_e32 v169, 8, v186
	v_mul_f32_e32 v216, 0x80000000, v214
	v_mul_f32_e32 v217, -2.0, v214
	v_mul_f32_e32 v218, 0xc0400000, v214
	v_mul_f32_e32 v219, -4.0, v214
	v_mul_f32_e32 v220, 0xc0a00000, v214
	v_mul_f32_e32 v221, 0xc0c00000, v214
	v_mul_f32_e32 v222, 0xc0e00000, v214
	v_mul_f32_e32 v223, 0xc1800000, v214
	v_mul_f32_e32 v224, 0xc1880000, v214
	v_mul_f32_e32 v225, 0xc1900000, v214
	v_mul_f32_e32 v226, 0xc1980000, v214
	v_mul_f32_e32 v227, 0xc1a00000, v214
	v_mul_f32_e32 v228, 0xc1a80000, v214
	v_mul_f32_e32 v229, 0xc1b00000, v214
	v_mul_f32_e32 v230, 0xc1b80000, v214
	v_cmp_eq_u32_e64 s[40:41], 0, v187
	s_lshl_b32 s59, s88, 2
	v_mov_b32_e32 v245, 0
	v_mov_b32_e32 v246, s98
	v_readlane_b32 s60, v254, 50
	v_readlane_b32 s61, v254, 38
	s_mov_b32 s88, s9
	v_mov_b64_e32 v[28:29], v[12:13]
	v_mov_b64_e32 v[26:27], v[10:11]
	v_mov_b64_e32 v[24:25], v[8:9]
	v_mov_b64_e32 v[22:23], v[6:7]
	v_mov_b64_e32 v[20:21], v[4:5]
	v_mov_b64_e32 v[18:19], v[2:3]
	v_mov_b64_e32 v[16:17], v[0:1]
	v_mov_b64_e32 v[44:45], v[12:13]
	v_mov_b64_e32 v[42:43], v[10:11]
	v_mov_b64_e32 v[40:41], v[8:9]
	v_mov_b64_e32 v[38:39], v[6:7]
	v_mov_b64_e32 v[36:37], v[4:5]
	v_mov_b64_e32 v[34:35], v[2:3]
	v_mov_b64_e32 v[32:33], v[0:1]
	v_mov_b64_e32 v[60:61], v[12:13]
	v_mov_b64_e32 v[58:59], v[10:11]
	v_mov_b64_e32 v[56:57], v[8:9]
	v_mov_b64_e32 v[54:55], v[6:7]
	v_mov_b64_e32 v[52:53], v[4:5]
	v_mov_b64_e32 v[50:51], v[2:3]
	v_mov_b64_e32 v[48:49], v[0:1]
	v_mov_b64_e32 v[76:77], v[12:13]
	v_mov_b64_e32 v[74:75], v[10:11]
	v_mov_b64_e32 v[72:73], v[8:9]
	v_mov_b64_e32 v[70:71], v[6:7]
	v_mov_b64_e32 v[68:69], v[4:5]
	v_mov_b64_e32 v[66:67], v[2:3]
	v_mov_b64_e32 v[64:65], v[0:1]
	s_waitcnt vmcnt(0) expcnt(0) lgkmcnt(0)
	s_barrier
	s_branch .LBB0_303
